# LRU conv-stage vmcnt waits relaxed (3/2) so they do not cover the previous unit's two HY stores
# speedup vs baseline: 1.0473x; 1.0052x over previous
; __device__ __forceinline__ unsigned pk_bf16(float lo, float hi) { typedef __bf16 b2_t __attribute__((ext_vector_type(2))); f32x2 v = {lo, hi}; b2_t b = __builtin_convertvector(v, b2_t); return __builtin_bit_cast(unsigned, b); }
; __device__ __forceinline__ void lru_phase(LAS unsigned char* lds, const bf16* XB, const bf16* Y, bf16* HY, const bf16* WRt, const bf16* WIt,
;         const float* convw, const float* convb, const float* br, const float* bi, const float* lam, unsigned long long* gran, int G, int bid, int wave_s) {
;     ...
;         LDS_BARRIER();
;         {
;             float cw[4][8], cb[8];
; #pragma unroll
;             for (int j = 0; j < 4; ++j) { const f32x4 c0v = *(const LAS f32x4*)(parL + j * 64 + cc), c1v = *(const LAS f32x4*)(parL + j * 64 + cc + 4);
;                 cw[j][0] = c0v[0]; cw[j][1] = c0v[1]; cw[j][2] = c0v[2]; cw[j][3] = c0v[3]; cw[j][4] = c1v[0]; cw[j][5] = c1v[1]; cw[j][6] = c1v[2]; cw[j][7] = c1v[3]; }
;             { const f32x4 c0v = *(const LAS f32x4*)(parL + 256 + cc), c1v = *(const LAS f32x4*)(parL + 256 + cc + 4);
;                 cb[0] = c0v[0]; cb[1] = c0v[1]; cb[2] = c0v[2]; cb[3] = c0v[3]; cb[4] = c1v[0]; cb[5] = c1v[1]; cb[6] = c1v[2]; cb[7] = c1v[3]; }
; #pragma unroll
;             for (int r = 0; r < 2; ++r) {
;                 const int t = st + 64 * r;
;                 float acc[8];
; #pragma unroll
;                 for (int e = 0; e < 8; ++e) acc[e] = cb[e];
; #pragma unroll
;                 for (int j = 0; j < 4; ++j) {
;                     const v4u x = xt[r][j];
;                     acc[0] += cw[j][0] * bf_lo(x.x); acc[1] += cw[j][1] * bf_hi(x.x); acc[2] += cw[j][2] * bf_lo(x.y); acc[3] += cw[j][3] * bf_hi(x.y);
;                     acc[4] += cw[j][4] * bf_lo(x.z); acc[5] += cw[j][5] * bf_hi(x.z); acc[6] += cw[j][6] * bf_lo(x.w); acc[7] += cw[j][7] * bf_hi(x.w);
;                 }
;                 *(LAS f32x4*)(xcF + t * 64 + cc) = (f32x4){acc[0], acc[1], acc[2], acc[3]}; *(LAS f32x4*)(xcF + t * 64 + cc + 4) = (f32x4){acc[4], acc[5], acc[6], acc[7]};
;                 v4u p; p.x = pk_bf16(acc[0], acc[1]); p.y = pk_bf16(acc[2], acc[3]); p.z = pk_bf16(acc[4], acc[5]); p.w = pk_bf16(acc[6], acc[7]);
;                 *(LAS v4u*)(xcB + t * KP + cc) = p;
;                 *(LAS v4u*)(yL + t * KP + cc) = yv[r];
;             }
;         }
;         if (unit + G < BATCH * 16 * NCH) LRU_LOAD_X(unit + G);
.LBB0_2122:
	s_waitcnt lgkmcnt(0)
	s_barrier
	ds_read_b128 v[0:3], v103
	ds_read_b128 v[4:7], v103 offset:16
	ds_read_b128 v[8:11], v103 offset:256
	ds_read_b128 v[12:15], v103 offset:272
	ds_read_b128 v[16:19], v103 offset:512
	ds_read_b128 v[20:23], v103 offset:528
	ds_read_b128 v[24:27], v104
	ds_read_b128 v[28:31], v103 offset:768
	ds_read_b128 v[88:91], v103 offset:784
	ds_read_b128 v[92:95], v104 offset:16
	s_waitcnt vmcnt(3)
	v_lshlrev_b32_e32 v96, 16, v40
	v_and_b32_e32 v97, 0xffff0000, v40
	s_waitcnt lgkmcnt(0)
	v_pk_fma_f32 v[96:97], v[0:1], v[96:97], v[24:25]
	v_lshlrev_b32_e32 v98, 16, v32
	v_and_b32_e32 v99, 0xffff0000, v32
	v_pk_fma_f32 v[96:97], v[8:9], v[98:99], v[96:97]
	v_lshlrev_b32_e32 v98, 16, v44
	v_and_b32_e32 v99, 0xffff0000, v44
	v_pk_fma_f32 v[96:97], v[16:17], v[98:99], v[96:97]
	v_lshlrev_b32_e32 v98, 16, v48
	v_and_b32_e32 v99, 0xffff0000, v48
	v_pk_fma_f32 v[96:97], v[28:29], v[98:99], v[96:97]
	v_lshlrev_b32_e32 v98, 16, v41
	v_and_b32_e32 v99, 0xffff0000, v41
	v_pk_fma_f32 v[98:99], v[2:3], v[98:99], v[26:27]
	v_lshlrev_b32_e32 v206, 16, v33
	v_and_b32_e32 v207, 0xffff0000, v33
	v_pk_fma_f32 v[98:99], v[10:11], v[206:207], v[98:99]
	v_lshlrev_b32_e32 v206, 16, v45
	v_and_b32_e32 v207, 0xffff0000, v45
	v_pk_fma_f32 v[98:99], v[18:19], v[206:207], v[98:99]
	v_lshlrev_b32_e32 v206, 16, v49
	v_and_b32_e32 v207, 0xffff0000, v49
	v_pk_fma_f32 v[98:99], v[30:31], v[206:207], v[98:99]
	v_lshlrev_b32_e32 v206, 16, v42
	v_and_b32_e32 v207, 0xffff0000, v42
	v_pk_fma_f32 v[206:207], v[4:5], v[206:207], v[92:93]
	v_lshlrev_b32_e32 v208, 16, v34
	v_and_b32_e32 v209, 0xffff0000, v34
	v_pk_fma_f32 v[206:207], v[12:13], v[208:209], v[206:207]
	v_lshlrev_b32_e32 v208, 16, v46
	v_and_b32_e32 v209, 0xffff0000, v46
	v_pk_fma_f32 v[206:207], v[20:21], v[208:209], v[206:207]
	v_lshlrev_b32_e32 v208, 16, v50
	v_and_b32_e32 v209, 0xffff0000, v50
	v_pk_fma_f32 v[206:207], v[88:89], v[208:209], v[206:207]
	v_lshlrev_b32_e32 v208, 16, v43
	v_and_b32_e32 v209, 0xffff0000, v43
	v_pk_fma_f32 v[208:209], v[6:7], v[208:209], v[94:95]
	v_lshlrev_b32_e32 v210, 16, v35
	v_and_b32_e32 v211, 0xffff0000, v35
	v_pk_fma_f32 v[208:209], v[14:15], v[210:211], v[208:209]
	v_lshlrev_b32_e32 v210, 16, v47
	v_and_b32_e32 v211, 0xffff0000, v47
	v_pk_fma_f32 v[208:209], v[22:23], v[210:211], v[208:209]
	v_lshlrev_b32_e32 v210, 16, v51
	v_and_b32_e32 v211, 0xffff0000, v51
	v_pk_fma_f32 v[208:209], v[90:91], v[210:211], v[208:209]
	v_add_u32_e32 v65, v105, v115
	ds_write_b128 v65, v[96:99]
	ds_write_b128 v65, v[206:209] offset:16
	v_cvt_pk_bf16_f32 v96, v96, v97
	v_cvt_pk_bf16_f32 v97, v98, v99
	v_cvt_pk_bf16_f32 v98, v206, v207
	v_cvt_pk_bf16_f32 v99, v208, v209
	v_add_u32_e32 v206, v106, v114
	ds_write_b128 v206, v[96:99]
	ds_write_b128 v116, v[36:39]
	s_waitcnt vmcnt(2)
	v_lshlrev_b32_e32 v96, 16, v56
	v_and_b32_e32 v97, 0xffff0000, v56
	v_pk_fma_f32 v[0:1], v[0:1], v[96:97], v[24:25]
	v_lshlrev_b32_e32 v24, 16, v60
	v_and_b32_e32 v25, 0xffff0000, v60
	v_pk_fma_f32 v[0:1], v[8:9], v[24:25], v[0:1]
	v_lshlrev_b32_e32 v8, 16, v66
	v_and_b32_e32 v9, 0xffff0000, v66
	v_pk_fma_f32 v[0:1], v[16:17], v[8:9], v[0:1]
	v_lshlrev_b32_e32 v8, 16, v70
	v_and_b32_e32 v9, 0xffff0000, v70
	v_pk_fma_f32 v[0:1], v[28:29], v[8:9], v[0:1]
	v_lshlrev_b32_e32 v8, 16, v57
	v_and_b32_e32 v9, 0xffff0000, v57
	v_pk_fma_f32 v[2:3], v[2:3], v[8:9], v[26:27]
	v_lshlrev_b32_e32 v8, 16, v61
	v_and_b32_e32 v9, 0xffff0000, v61
	v_pk_fma_f32 v[2:3], v[10:11], v[8:9], v[2:3]
	v_lshlrev_b32_e32 v8, 16, v67
	v_and_b32_e32 v9, 0xffff0000, v67
	v_pk_fma_f32 v[2:3], v[18:19], v[8:9], v[2:3]
	v_lshlrev_b32_e32 v8, 16, v71
	v_and_b32_e32 v9, 0xffff0000, v71
	v_pk_fma_f32 v[2:3], v[30:31], v[8:9], v[2:3]
	v_lshlrev_b32_e32 v8, 16, v58
	v_and_b32_e32 v9, 0xffff0000, v58
	v_pk_fma_f32 v[4:5], v[4:5], v[8:9], v[92:93]
	v_lshlrev_b32_e32 v8, 16, v62
	v_and_b32_e32 v9, 0xffff0000, v62
	v_pk_fma_f32 v[4:5], v[12:13], v[8:9], v[4:5]
	v_lshlrev_b32_e32 v8, 16, v68
	v_and_b32_e32 v9, 0xffff0000, v68
	v_pk_fma_f32 v[4:5], v[20:21], v[8:9], v[4:5]
	v_lshlrev_b32_e32 v8, 16, v72
	v_and_b32_e32 v9, 0xffff0000, v72
	v_pk_fma_f32 v[4:5], v[88:89], v[8:9], v[4:5]
	v_lshlrev_b32_e32 v8, 16, v59
	v_and_b32_e32 v9, 0xffff0000, v59
	v_pk_fma_f32 v[6:7], v[6:7], v[8:9], v[94:95]
	v_lshlrev_b32_e32 v8, 16, v63
	v_and_b32_e32 v9, 0xffff0000, v63
	v_pk_fma_f32 v[6:7], v[14:15], v[8:9], v[6:7]
	v_lshlrev_b32_e32 v8, 16, v69
	v_and_b32_e32 v9, 0xffff0000, v69
	s_add_i32 s93, s84, s46
	v_pk_fma_f32 v[6:7], v[22:23], v[8:9], v[6:7]
	v_lshlrev_b32_e32 v8, 16, v73
	v_and_b32_e32 v9, 0xffff0000, v73
	s_cmpk_gt_i32 s93, 0x7ff
	v_pk_fma_f32 v[6:7], v[90:91], v[8:9], v[6:7]
	s_cselect_b64 s[58:59], -1, 0
	ds_write_b128 v190, v[0:3]
	ds_write_b128 v190, v[4:7] offset:16
	v_cvt_pk_bf16_f32 v0, v0, v1
	v_cvt_pk_bf16_f32 v1, v2, v3
	v_cvt_pk_bf16_f32 v2, v4, v5
	v_cvt_pk_bf16_f32 v3, v6, v7
	s_and_b64 vcc, exec, s[58:59]
	ds_write_b128 v117, v[0:3]
	ds_write_b128 v118, v[52:55]
	s_cbranch_vccnz .LBB0_2140
	s_and_b32 s6, s93, 0xffffff80
	s_lshl_b32 s7, s93, 7
	s_and_b32 s60, s7, 0x3800
	v_add_u32_e32 v8, s6, v100
	v_add_u32_e32 v4, s60, v8
	s_and_b32 s6, s7, 0x780
	s_mov_b32 s7, s42
	v_ashrrev_i32_e32 v5, 31, v4
	v_lshl_add_u64 v[6:7], v[76:77], 0, s[6:7]
	v_lshlrev_b64 v[0:1], 11, v[4:5]
	v_lshl_add_u64 v[0:1], v[6:7], 0, v[0:1]
	global_load_dwordx4 v[36:39], v[0:1], off
	v_mov_b32_e32 v34, v64
	v_mov_b32_e32 v35, v64
	v_lshl_add_u64 v[0:1], v[78:79], 0, s[6:7]
	s_add_i32 s6, s60, -3
	v_mov_b32_e32 v32, v64
	v_mov_b32_e32 v33, v64
	v_mov_b64_e32 v[42:43], v[34:35]
	v_cmp_lt_i32_e32 vcc, 2, v8
	v_add_u32_e32 v2, s6, v8
	v_mov_b64_e32 v[40:41], v[32:33]
	s_and_saveexec_b64 s[60:61], vcc
	s_cbranch_execz .LBB0_2125
	v_mov_b32_e32 v3, v64
	v_lshlrev_b64 v[10:11], 11, v[2:3]
	v_lshl_add_u64 v[10:11], v[0:1], 0, v[10:11]
	global_load_dwordx4 v[40:43], v[10:11], off
